# speedup vs baseline: 1.0093x; 1.0093x over previous
; __device__ __forceinline__ void phase0(const Params& p, unsigned char* smem) {
;     ...
;             const int kt = t / ntn, nt = t % ntn, k0 = kt * 64, n0 = nt * 64;
;             {
;                 const int r = tid >> 4, c4 = (tid & 15) * 4, n = n0 + c4;
; #pragma unroll
;                 for (int rr = r; rr < 64; rr += 32) {
;                     f32x4 v = {0, 0, 0, 0};
;                     if (n < Ns) v = *(const f32x4*)(src + (size_t)(k0 + rr) * Ns + n);
;                     ldsf[rr * 65 + c4] = v[0]; ldsf[rr * 65 + c4 + 1] = v[1]; ldsf[rr * 65 + c4 + 2] = v[2]; ldsf[rr * 65 + c4 + 3] = v[3];
;                 }
.LBB0_23:
	v_mov_b32_e32 v4, 0
	v_mov_b32_e32 v5, 0
	v_mov_b32_e32 v6, 0
	v_mov_b32_e32 v7, 0
	v_mov_b32_e32 v12, 0
	v_mov_b32_e32 v13, 0
	v_mov_b32_e32 v14, 0
	v_mov_b32_e32 v15, 0
	s_and_saveexec_b64 s[20:21], vcc
	s_cbranch_execz .Lp0_noload
	v_lshl_add_u64 v[16:17], v[8:9], 0, s[26:27]
	global_load_dwordx4 v[4:7], v[8:9], off
	global_load_dwordx4 v[12:15], v[16:17], off
.Lp0_noload:
	s_or_b64 exec, exec, s[20:21]
	s_waitcnt vmcnt(1)
	ds_write2_b32 v3, v4, v5 offset1:1
	ds_write2_b32 v3, v6, v7 offset0:2 offset1:3
	v_add_u32_e32 v3, 0x2080, v3
	s_waitcnt vmcnt(0)
	ds_write2_b32 v3, v12, v13 offset1:1
	ds_write2_b32 v3, v14, v15 offset0:2 offset1:3

; __device__ __forceinline__ void phase_norm(const float* xin, const float* g, const float* mod, int shift_off, int scale_off, bf16_t* hout) {
;     int tid_o = threadIdx.x; asm volatile("" : "+v"(tid_o));
;     const int lane = tid_o & 63, wid = tid_o >> 6, nw = gridDim.x * 8;
;     for (int row = blockIdx.x * 8 + wid; row < NTOK; row += nw) {
;         const int b = row >> 13;
;         const float* xr = xin + (size_t)row * DM;
;         f32x4 v[8]; float ss = 0.f;
; #pragma unroll
;         for (int i = 0; i < 8; ++i) { v[i] = *(const f32x4*)(xr + i * 256 + lane * 4); ss += v[i][0] * v[i][0] + v[i][1] * v[i][1] + v[i][2] * v[i][2] + v[i][3] * v[i][3]; }
;         ss = wave_sum(ss);
;         const float rstd = rsqrtf(ss * (1.0f / DM) + 1e-6f);
;         const float* mb = mod + (size_t)b * 6 * DM;
; #pragma unroll
;         for (int i = 0; i < 8; ++i) {
;             const int col = i * 256 + lane * 4;
;             const f32x4 g4 = *(const f32x4*)(g + col), sc4 = *(const f32x4*)(mb + scale_off + col), sh4 = *(const f32x4*)(mb + shift_off + col);
.LBB0_54:
	s_mov_b64 s[14:15], s[0:1]
	v_mov_b32_e32 v0, v166
	s_nop 0
	v_ashrrev_i32_e32 v1, 6, v0
	v_add_u32_e32 v34, s70, v1
	v_cmp_gt_i32_e32 vcc, s19, v34
	s_and_saveexec_b64 s[12:13], vcc
	s_cbranch_execz .LBB0_53
	v_lshlrev_b32_e32 v1, 2, v0
	v_cmp_lt_i32_e32 vcc, v169, v168
	v_and_b32_e32 v2, 0xfc, v1
	s_load_dwordx2 s[4:5], s[14:15], 0x80
	s_load_dwordx2 s[16:17], s[14:15], 0x0
	s_load_dwordx2 s[22:23], s[14:15], 0x20
	v_cndmask_b32_e32 v1, v167, v169, vcc
	v_cmp_lt_i32_e32 vcc, v170, v168
	v_lshlrev_b32_e32 v72, 2, v1
	v_ashrrev_i32_e32 v35, 31, v34
	v_cndmask_b32_e32 v1, v167, v170, vcc
	v_cmp_lt_i32_e32 vcc, v171, v168
	v_lshlrev_b32_e32 v73, 2, v1
	v_lshlrev_b64 v[18:19], 12, v[34:35]
	v_cndmask_b32_e32 v1, v167, v171, vcc
	v_cmp_lt_i32_e32 vcc, v172, v168
	v_lshlrev_b32_e32 v74, 2, v1
	v_and_b32_e32 v3, 63, v0
	v_cndmask_b32_e32 v1, v167, v172, vcc
	v_cmp_lt_i32_e32 vcc, v173, v168
	v_lshlrev_b32_e32 v75, 2, v1
	v_lshlrev_b32_e32 v32, 2, v2
	v_cndmask_b32_e32 v1, v167, v173, vcc
	v_cmp_lt_i32_e32 vcc, v174, v168
	v_lshlrev_b32_e32 v76, 2, v1
	v_or_b32_e32 v10, 0x400, v2
	v_cndmask_b32_e32 v1, v167, v174, vcc
	v_lshl_or_b32 v18, v3, 3, v18
	v_lshlrev_b32_e32 v77, 2, v1
	s_waitcnt lgkmcnt(0)
	v_lshl_add_u64 v[36:37], s[22:23], 0, v[32:33]
	v_lshlrev_b32_e32 v32, 2, v10
	v_or_b32_e32 v12, 0x500, v2
	v_lshl_add_u64 v[0:1], s[4:5], 0, v[18:19]
	v_lshl_add_u64 v[38:39], s[22:23], 0, v[32:33]
	v_lshlrev_b32_e32 v32, 2, v12
	v_or_b32_e32 v14, 0x600, v2
	v_lshl_add_u64 v[46:47], v[0:1], 0, s[6:7]
	v_lshlrev_b64 v[0:1], 13, v[34:35]
	v_lshl_add_u64 v[40:41], s[22:23], 0, v[32:33]
	v_lshlrev_b32_e32 v32, 2, v14
	v_or_b32_e32 v16, 0x700, v2
	v_lshl_or_b32 v0, v3, 4, v0
	s_add_u32 s14, s4, 0x6300000
	v_or_b32_e32 v4, 0x100, v2
	v_or_b32_e32 v6, 0x200, v2
	v_or_b32_e32 v8, 0x300, v2
	v_lshl_add_u64 v[42:43], s[22:23], 0, v[32:33]
	v_lshlrev_b32_e32 v32, 2, v16
	v_lshl_add_u64 v[0:1], s[16:17], 0, v[0:1]
	s_addc_u32 s15, s5, 0
	v_lshl_add_u64 v[44:45], s[22:23], 0, v[32:33]
	v_lshl_add_u64 v[48:49], v[0:1], 0, s[8:9]
	s_mov_b64 s[16:17], 0
	v_lshlrev_b32_e32 v32, 2, v2
	v_lshlrev_b32_e32 v50, 2, v4
	v_lshlrev_b32_e32 v52, 2, v6
	v_lshlrev_b32_e32 v54, 2, v8
	v_lshlrev_b32_e32 v56, 2, v10
	v_lshlrev_b32_e32 v58, 2, v12
	v_lshlrev_b32_e32 v60, 2, v14
	v_lshlrev_b32_e32 v62, 2, v16
	v_mov_b32_e32 v51, v33
	v_mov_b32_e32 v53, v33
	v_mov_b32_e32 v55, v33
	v_mov_b32_e32 v57, v33
	v_mov_b32_e32 v59, v33
	v_mov_b32_e32 v61, v33
	v_mov_b32_e32 v63, v33
	s_mov_b32 s98, -1
.LBB0_56:
	v_ashrrev_i32_e32 v35, 13, v34
	s_nop 0
	v_readfirstlane_b32 s99, v35
	s_cmp_eq_u32 s99, s98
	s_cbranch_scc1 .Lnorm1_params_ok
	s_mov_b32 s98, s99
	v_mul_i32_i24_e32 v160, 6, v35
	v_ashrrev_i32_e32 v161, 31, v160
	v_lshlrev_b64 v[160:161], 13, v[160:161]
	v_lshl_add_u64 v[160:161], s[14:15], 0, v[160:161]
	v_lshl_add_u64 v[162:163], v[160:161], 0, s[10:11]
	v_lshl_add_u64 v[152:153], v[162:163], 0, v[32:33]
	v_lshl_add_u64 v[154:155], v[160:161], 0, v[32:33]
	v_lshl_add_u64 v[156:157], v[162:163], 0, v[56:57]
	v_lshl_add_u64 v[158:159], v[160:161], 0, v[56:57]
	global_load_dwordx4 v[112:115], v[36:37], off
	global_load_dwordx4 v[116:119], v[36:37], off offset:1024
	global_load_dwordx4 v[120:123], v[36:37], off offset:2048
	global_load_dwordx4 v[124:127], v[36:37], off offset:3072
	global_load_dwordx4 v[128:131], v[38:39], off
	global_load_dwordx4 v[132:135], v[38:39], off offset:1024
	global_load_dwordx4 v[136:139], v[38:39], off offset:2048
	global_load_dwordx4 v[140:143], v[38:39], off offset:3072
	global_load_dwordx4 v[176:179], v[152:153], off
	global_load_dwordx4 v[180:183], v[152:153], off offset:1024
	global_load_dwordx4 v[184:187], v[152:153], off offset:2048
	global_load_dwordx4 v[188:191], v[152:153], off offset:3072
	global_load_dwordx4 v[192:195], v[156:157], off
	global_load_dwordx4 v[196:199], v[156:157], off offset:1024
	global_load_dwordx4 v[200:203], v[156:157], off offset:2048
	global_load_dwordx4 v[204:207], v[156:157], off offset:3072
	global_load_dwordx4 v[208:211], v[154:155], off
	global_load_dwordx4 v[212:215], v[154:155], off offset:1024
	global_load_dwordx4 v[216:219], v[154:155], off offset:2048
	global_load_dwordx4 v[220:223], v[154:155], off offset:3072
	global_load_dwordx4 v[224:227], v[158:159], off
	global_load_dwordx4 v[228:231], v[158:159], off offset:1024
	global_load_dwordx4 v[144:147], v[158:159], off offset:2048
	global_load_dwordx4 v[148:151], v[158:159], off offset:3072
; __device__ __forceinline__ unsigned cvt_pk_bf16(float lo, float hi) { unsigned r; asm volatile("v_cvt_pk_bf16_f32 %0, %1, %2" : "=v"(r) : "v"(lo), "v"(hi)); return r; }
; __device__ __forceinline__ void phase_norm(const float* xin, const float* g, const float* mod, int shift_off, int scale_off, bf16_t* hout) {
;     ...
;     for (int row = blockIdx.x * 8 + wid; row < NTOK; row += nw) {
;         const int b = row >> 13;
;         const float* xr = xin + (size_t)row * DM;
;         f32x4 v[8]; float ss = 0.f;
; #pragma unroll
;         for (int i = 0; i < 8; ++i) { v[i] = *(const f32x4*)(xr + i * 256 + lane * 4); ss += v[i][0] * v[i][0] + v[i][1] * v[i][1] + v[i][2] * v[i][2] + v[i][3] * v[i][3]; }
;         ss = wave_sum(ss);
;         const float rstd = rsqrtf(ss * (1.0f / DM) + 1e-6f);
;         const float* mb = mod + (size_t)b * 6 * DM;
; #pragma unroll
;         for (int i = 0; i < 8; ++i) {
;             const int col = i * 256 + lane * 4;
;             const f32x4 g4 = *(const f32x4*)(g + col), sc4 = *(const f32x4*)(mb + scale_off + col), sh4 = *(const f32x4*)(mb + shift_off + col);
;             f32x4 y = (v[i] * rstd) * g4; y = y * (sc4 + 1.0f) + sh4;
;             u32x2 w; w.x = cvt_pk_bf16(y[0], y[1]); w.y = cvt_pk_bf16(y[2], y[3]);
;             *(u32x2*)(hout + (size_t)row * DM + col) = w;
;         }
;     }
.Lnorm1_params_ok:
	global_load_dwordx4 v[24:27], v[48:49], off offset:-4096
	global_load_dwordx4 v[28:31], v[48:49], off offset:-3072
	global_load_dwordx4 v[20:23], v[48:49], off offset:-2048
	global_load_dwordx4 v[16:19], v[48:49], off offset:-1024
	global_load_dwordx4 v[12:15], v[48:49], off
	global_load_dwordx4 v[8:11], v[48:49], off offset:1024
	global_load_dwordx4 v[4:7], v[48:49], off offset:2048
	global_load_dwordx4 v[0:3], v[48:49], off offset:3072
	v_add_u32_e32 v34, s48, v34
	v_lshl_add_u64 v[48:49], v[48:49], 0, s[52:53]
	s_waitcnt vmcnt(7)
	v_mul_f32_e32 v35, v24, v24
	v_fmac_f32_e32 v35, v25, v25
	v_fmac_f32_e32 v35, v26, v26
	v_fmac_f32_e32 v35, v27, v27
	s_waitcnt vmcnt(6)
	v_mul_f32_e32 v175, v28, v28
	v_fmac_f32_e32 v175, v29, v29
	v_fmac_f32_e32 v175, v30, v30
	v_fmac_f32_e32 v175, v31, v31
	s_waitcnt vmcnt(5)
	v_fmac_f32_e32 v35, v20, v20
	v_fmac_f32_e32 v35, v21, v21
	v_fmac_f32_e32 v35, v22, v22
	v_fmac_f32_e32 v35, v23, v23
	s_waitcnt vmcnt(4)
	v_fmac_f32_e32 v175, v16, v16
	v_fmac_f32_e32 v175, v17, v17
	v_fmac_f32_e32 v175, v18, v18
	v_fmac_f32_e32 v175, v19, v19
	s_waitcnt vmcnt(3)
	v_fmac_f32_e32 v35, v12, v12
	v_fmac_f32_e32 v35, v13, v13
	v_fmac_f32_e32 v35, v14, v14
	v_fmac_f32_e32 v35, v15, v15
	s_waitcnt vmcnt(2)
	v_fmac_f32_e32 v175, v8, v8
	v_fmac_f32_e32 v175, v9, v9
	v_fmac_f32_e32 v175, v10, v10
	v_fmac_f32_e32 v175, v11, v11
	s_waitcnt vmcnt(1)
	v_fmac_f32_e32 v35, v4, v4
	v_fmac_f32_e32 v35, v5, v5
	v_fmac_f32_e32 v35, v6, v6
	v_fmac_f32_e32 v35, v7, v7
	s_waitcnt vmcnt(0)
	v_fmac_f32_e32 v175, v0, v0
	v_fmac_f32_e32 v175, v1, v1
	v_fmac_f32_e32 v175, v2, v2
	v_fmac_f32_e32 v175, v3, v3
	v_add_f32_e32 v35, v35, v175
	ds_bpermute_b32 v68, v72, v35
	s_waitcnt lgkmcnt(0)
	v_add_f32_e32 v35, v35, v68
	ds_bpermute_b32 v68, v73, v35
	s_waitcnt lgkmcnt(0)
	v_add_f32_e32 v35, v35, v68
	ds_bpermute_b32 v68, v74, v35
	s_waitcnt lgkmcnt(0)
	v_add_f32_e32 v35, v35, v68
	ds_bpermute_b32 v68, v75, v35
	s_waitcnt lgkmcnt(0)
	v_add_f32_e32 v35, v35, v68
	ds_bpermute_b32 v68, v76, v35
	s_waitcnt lgkmcnt(0)
	v_add_f32_e32 v35, v35, v68
	ds_bpermute_b32 v68, v77, v35
	s_waitcnt lgkmcnt(0)
	v_add_f32_e32 v35, v35, v68
	v_fmamk_f32 v35, v35, 0x3a000000, v69
	v_mul_f32_e32 v68, 0x4b800000, v35
	v_cmp_gt_f32_e32 vcc, s20, v35
	s_nop 1
	v_cndmask_b32_e32 v35, v35, v68, vcc
	v_rsq_f32_e32 v35, v35
	s_nop 0
	v_mul_f32_e32 v68, 0x45800000, v35
	v_cndmask_b32_e32 v68, v35, v68, vcc
	v_pk_mul_f32 v[24:25], v[24:25], v[68:69] op_sel_hi:[1,0]
	v_pk_mul_f32 v[26:27], v[26:27], v[68:69] op_sel_hi:[1,0]
	v_pk_mul_f32 v[24:25], v[112:113], v[24:25]
	v_pk_mul_f32 v[26:27], v[114:115], v[26:27]
	v_pk_add_f32 v[164:165], v[176:177], 1.0 op_sel_hi:[1,0]
	v_pk_add_f32 v[110:111], v[178:179], 1.0 op_sel_hi:[1,0]
	v_pk_fma_f32 v[24:25], v[164:165], v[24:25], v[208:209]
	v_pk_fma_f32 v[26:27], v[110:111], v[26:27], v[210:211]
	v_cvt_pk_bf16_f32 v24, v24, v25
	v_cvt_pk_bf16_f32 v25, v26, v27
	global_store_dwordx2 v[46:47], v[24:25], off
	v_pk_mul_f32 v[28:29], v[28:29], v[68:69] op_sel_hi:[1,0]
	v_pk_mul_f32 v[30:31], v[30:31], v[68:69] op_sel_hi:[1,0]
	v_pk_mul_f32 v[28:29], v[116:117], v[28:29]
	v_pk_mul_f32 v[30:31], v[118:119], v[30:31]
	v_pk_add_f32 v[164:165], v[180:181], 1.0 op_sel_hi:[1,0]
	v_pk_add_f32 v[110:111], v[182:183], 1.0 op_sel_hi:[1,0]
	v_pk_fma_f32 v[28:29], v[164:165], v[28:29], v[212:213]
	v_pk_fma_f32 v[30:31], v[110:111], v[30:31], v[214:215]
	v_cvt_pk_bf16_f32 v28, v28, v29
	v_cvt_pk_bf16_f32 v29, v30, v31
	global_store_dwordx2 v[46:47], v[28:29], off offset:512
	v_pk_mul_f32 v[20:21], v[20:21], v[68:69] op_sel_hi:[1,0]
	v_pk_mul_f32 v[22:23], v[22:23], v[68:69] op_sel_hi:[1,0]
	v_pk_mul_f32 v[20:21], v[120:121], v[20:21]
	v_pk_mul_f32 v[22:23], v[122:123], v[22:23]
	v_pk_add_f32 v[164:165], v[184:185], 1.0 op_sel_hi:[1,0]
	v_pk_add_f32 v[110:111], v[186:187], 1.0 op_sel_hi:[1,0]
	v_pk_fma_f32 v[20:21], v[164:165], v[20:21], v[216:217]
	v_pk_fma_f32 v[22:23], v[110:111], v[22:23], v[218:219]
	v_cvt_pk_bf16_f32 v20, v20, v21
	v_cvt_pk_bf16_f32 v21, v22, v23
	global_store_dwordx2 v[46:47], v[20:21], off offset:1024
	v_pk_mul_f32 v[16:17], v[16:17], v[68:69] op_sel_hi:[1,0]
	v_pk_mul_f32 v[18:19], v[18:19], v[68:69] op_sel_hi:[1,0]
	v_pk_mul_f32 v[16:17], v[124:125], v[16:17]
	v_pk_mul_f32 v[18:19], v[126:127], v[18:19]
	v_pk_add_f32 v[164:165], v[188:189], 1.0 op_sel_hi:[1,0]
	v_pk_add_f32 v[110:111], v[190:191], 1.0 op_sel_hi:[1,0]
	v_pk_fma_f32 v[16:17], v[164:165], v[16:17], v[220:221]
	v_pk_fma_f32 v[18:19], v[110:111], v[18:19], v[222:223]
	v_cvt_pk_bf16_f32 v16, v16, v17
	v_cvt_pk_bf16_f32 v17, v18, v19
	global_store_dwordx2 v[46:47], v[16:17], off offset:1536
	v_pk_mul_f32 v[12:13], v[12:13], v[68:69] op_sel_hi:[1,0]
	v_pk_mul_f32 v[14:15], v[14:15], v[68:69] op_sel_hi:[1,0]
	v_pk_mul_f32 v[12:13], v[128:129], v[12:13]
	v_pk_mul_f32 v[14:15], v[130:131], v[14:15]
	v_pk_add_f32 v[164:165], v[192:193], 1.0 op_sel_hi:[1,0]
	v_pk_add_f32 v[110:111], v[194:195], 1.0 op_sel_hi:[1,0]
	v_pk_fma_f32 v[12:13], v[164:165], v[12:13], v[224:225]
	v_pk_fma_f32 v[14:15], v[110:111], v[14:15], v[226:227]
	v_cvt_pk_bf16_f32 v12, v12, v13
	v_cvt_pk_bf16_f32 v13, v14, v15
	global_store_dwordx2 v[46:47], v[12:13], off offset:2048
	v_pk_mul_f32 v[8:9], v[8:9], v[68:69] op_sel_hi:[1,0]
	v_pk_mul_f32 v[10:11], v[10:11], v[68:69] op_sel_hi:[1,0]
	v_pk_mul_f32 v[8:9], v[132:133], v[8:9]
	v_pk_mul_f32 v[10:11], v[134:135], v[10:11]
	v_pk_add_f32 v[164:165], v[196:197], 1.0 op_sel_hi:[1,0]
	v_pk_add_f32 v[110:111], v[198:199], 1.0 op_sel_hi:[1,0]
	v_pk_fma_f32 v[8:9], v[164:165], v[8:9], v[228:229]
	v_pk_fma_f32 v[10:11], v[110:111], v[10:11], v[230:231]
	v_cvt_pk_bf16_f32 v8, v8, v9
	v_cvt_pk_bf16_f32 v9, v10, v11
	global_store_dwordx2 v[46:47], v[8:9], off offset:2560
	v_pk_mul_f32 v[4:5], v[4:5], v[68:69] op_sel_hi:[1,0]
	v_pk_mul_f32 v[6:7], v[6:7], v[68:69] op_sel_hi:[1,0]
	v_pk_mul_f32 v[4:5], v[136:137], v[4:5]
	v_pk_mul_f32 v[6:7], v[138:139], v[6:7]
	v_pk_add_f32 v[164:165], v[200:201], 1.0 op_sel_hi:[1,0]
	v_pk_add_f32 v[110:111], v[202:203], 1.0 op_sel_hi:[1,0]
	v_pk_fma_f32 v[4:5], v[164:165], v[4:5], v[144:145]
	v_pk_fma_f32 v[6:7], v[110:111], v[6:7], v[146:147]
	v_cvt_pk_bf16_f32 v4, v4, v5
	v_cvt_pk_bf16_f32 v5, v6, v7
	global_store_dwordx2 v[46:47], v[4:5], off offset:3072
	v_pk_mul_f32 v[0:1], v[0:1], v[68:69] op_sel_hi:[1,0]
	v_pk_mul_f32 v[2:3], v[2:3], v[68:69] op_sel_hi:[1,0]
	v_pk_mul_f32 v[0:1], v[140:141], v[0:1]
	v_pk_mul_f32 v[2:3], v[142:143], v[2:3]
	v_pk_add_f32 v[164:165], v[204:205], 1.0 op_sel_hi:[1,0]
	v_pk_add_f32 v[110:111], v[206:207], 1.0 op_sel_hi:[1,0]
	v_pk_fma_f32 v[0:1], v[164:165], v[0:1], v[148:149]
	v_pk_fma_f32 v[2:3], v[110:111], v[2:3], v[150:151]
	v_cvt_pk_bf16_f32 v0, v0, v1
	v_cvt_pk_bf16_f32 v1, v2, v3
	global_store_dwordx2 v[46:47], v[0:1], off offset:3584
	v_cmp_lt_i32_e32 vcc, s21, v34
	s_or_b64 s[16:17], vcc, s[16:17]
	v_lshl_add_u64 v[46:47], v[46:47], 0, s[50:51]
	s_andn2_b64 exec, exec, s[16:17]
	s_cbranch_execnz .LBB0_56
	s_branch .LBB0_53

; __device__ __forceinline__ void phase_norm(const float* xin, const float* g, const float* mod, int shift_off, int scale_off, bf16_t* hout) {
;     int tid_o = threadIdx.x; asm volatile("" : "+v"(tid_o));
;     const int lane = tid_o & 63, wid = tid_o >> 6, nw = gridDim.x * 8;
;     for (int row = blockIdx.x * 8 + wid; row < NTOK; row += nw) {
;         const int b = row >> 13;
;         const float* xr = xin + (size_t)row * DM;
;         f32x4 v[8]; float ss = 0.f;
; #pragma unroll
;         for (int i = 0; i < 8; ++i) { v[i] = *(const f32x4*)(xr + i * 256 + lane * 4); ss += v[i][0] * v[i][0] + v[i][1] * v[i][1] + v[i][2] * v[i][2] + v[i][3] * v[i][3]; }
;         ss = wave_sum(ss);
;         const float rstd = rsqrtf(ss * (1.0f / DM) + 1e-6f);
;         const float* mb = mod + (size_t)b * 6 * DM;
; #pragma unroll
;         for (int i = 0; i < 8; ++i) {
;             const int col = i * 256 + lane * 4;
;             const f32x4 g4 = *(const f32x4*)(g + col), sc4 = *(const f32x4*)(mb + scale_off + col), sh4 = *(const f32x4*)(mb + shift_off + col);
.LBB0_1896:
	s_mov_b64 s[26:27], s[0:1]
	v_mov_b32_e32 v0, v166
	s_nop 0
	v_ashrrev_i32_e32 v1, 6, v0
	v_add_u32_e32 v30, s70, v1
	v_cmp_gt_i32_e32 vcc, s30, v30
	s_and_saveexec_b64 s[24:25], vcc
	s_cbranch_execz .LBB0_1895
	v_lshlrev_b32_e32 v1, 2, v0
	v_cmp_lt_i32_e32 vcc, v169, v168
	v_and_b32_e32 v2, 0xfc, v1
	s_load_dwordx4 s[8:11], s[26:27], 0x78
	s_load_dwordx2 s[4:5], s[26:27], 0x28
	v_cndmask_b32_e32 v1, v167, v169, vcc
	v_cmp_lt_i32_e32 vcc, v170, v168
	v_lshlrev_b32_e32 v66, 2, v1
	v_ashrrev_i32_e32 v31, 31, v30
	v_cndmask_b32_e32 v1, v167, v170, vcc
	v_cmp_lt_i32_e32 vcc, v171, v168
	v_lshlrev_b32_e32 v67, 2, v1
	v_lshlrev_b64 v[18:19], 12, v[30:31]
	v_cndmask_b32_e32 v1, v167, v171, vcc
	v_cmp_lt_i32_e32 vcc, v172, v168
	s_waitcnt vmcnt(4)
	v_lshlrev_b32_e32 v68, 2, v1
	v_and_b32_e32 v3, 63, v0
	v_cndmask_b32_e32 v1, v167, v172, vcc
	v_cmp_lt_i32_e32 vcc, v173, v168
	v_lshlrev_b32_e32 v69, 2, v1
	v_lshlrev_b32_e32 v28, 2, v2
	v_cndmask_b32_e32 v1, v167, v173, vcc
	v_cmp_lt_i32_e32 vcc, v174, v168
	v_lshlrev_b32_e32 v70, 2, v1
	v_or_b32_e32 v10, 0x400, v2
	v_cndmask_b32_e32 v1, v167, v174, vcc
	v_lshl_or_b32 v18, v3, 3, v18
	v_lshlrev_b32_e32 v71, 2, v1
	s_waitcnt lgkmcnt(0)
	v_lshl_add_u64 v[32:33], s[4:5], 0, v[28:29]
	v_lshlrev_b32_e32 v28, 2, v10
	v_or_b32_e32 v12, 0x500, v2
	v_lshl_add_u64 v[0:1], s[10:11], 0, v[18:19]
	v_lshl_add_u64 v[34:35], s[4:5], 0, v[28:29]
	v_lshlrev_b32_e32 v28, 2, v12
	v_or_b32_e32 v14, 0x600, v2
	v_lshl_add_u64 v[42:43], v[0:1], 0, s[12:13]
	v_lshlrev_b64 v[0:1], 13, v[30:31]
	v_lshl_add_u64 v[36:37], s[4:5], 0, v[28:29]
	v_lshlrev_b32_e32 v28, 2, v14
	v_or_b32_e32 v16, 0x700, v2
	v_lshl_or_b32 v0, v3, 4, v0
	s_add_u32 s26, s10, 0x6300000
	v_or_b32_e32 v4, 0x100, v2
	v_or_b32_e32 v6, 0x200, v2
	v_or_b32_e32 v8, 0x300, v2
	v_lshl_add_u64 v[38:39], s[4:5], 0, v[28:29]
	v_lshlrev_b32_e32 v28, 2, v16
	v_lshl_add_u64 v[0:1], s[8:9], 0, v[0:1]
	s_addc_u32 s27, s11, 0
	v_lshl_add_u64 v[40:41], s[4:5], 0, v[28:29]
	v_lshl_add_u64 v[44:45], v[0:1], 0, s[14:15]
	s_mov_b64 s[8:9], 0
	v_lshlrev_b32_e32 v28, 2, v2
	v_lshlrev_b32_e32 v46, 2, v4
	v_lshlrev_b32_e32 v48, 2, v6
	v_lshlrev_b32_e32 v50, 2, v8
	v_lshlrev_b32_e32 v52, 2, v10
	v_lshlrev_b32_e32 v54, 2, v12
	v_lshlrev_b32_e32 v56, 2, v14
	v_lshlrev_b32_e32 v58, 2, v16
	v_mov_b32_e32 v47, v29
	v_mov_b32_e32 v49, v29
	v_mov_b32_e32 v51, v29
	v_mov_b32_e32 v53, v29
	v_mov_b32_e32 v55, v29
	v_mov_b32_e32 v57, v29
	v_mov_b32_e32 v59, v29
	s_mov_b32 s98, -1
.LBB0_1898:
	v_ashrrev_i32_e32 v31, 13, v30
	s_nop 0
	v_readfirstlane_b32 s99, v31
	s_cmp_eq_u32 s99, s98
	s_cbranch_scc1 .Lnorm2_params_ok
	s_mov_b32 s98, s99
	v_mul_i32_i24_e32 v160, 6, v31
	v_ashrrev_i32_e32 v161, 31, v160
	v_lshlrev_b64 v[160:161], 13, v[160:161]
	v_lshl_add_u64 v[160:161], s[26:27], 0, v[160:161]
	v_lshl_add_u64 v[162:163], v[160:161], 0, s[20:21]
	v_lshl_add_u64 v[160:161], v[160:161], 0, s[22:23]
	v_lshl_add_u64 v[152:153], v[162:163], 0, v[28:29]
	v_lshl_add_u64 v[154:155], v[160:161], 0, v[28:29]
	v_lshl_add_u64 v[156:157], v[162:163], 0, v[52:53]
	v_lshl_add_u64 v[158:159], v[160:161], 0, v[52:53]
	global_load_dwordx4 v[112:115], v[32:33], off
	global_load_dwordx4 v[116:119], v[32:33], off offset:1024
	global_load_dwordx4 v[120:123], v[32:33], off offset:2048
	global_load_dwordx4 v[124:127], v[32:33], off offset:3072
	global_load_dwordx4 v[128:131], v[34:35], off
	global_load_dwordx4 v[132:135], v[34:35], off offset:1024
	global_load_dwordx4 v[136:139], v[34:35], off offset:2048
	global_load_dwordx4 v[140:143], v[34:35], off offset:3072
	global_load_dwordx4 v[176:179], v[152:153], off
	global_load_dwordx4 v[180:183], v[152:153], off offset:1024
	global_load_dwordx4 v[184:187], v[152:153], off offset:2048
	global_load_dwordx4 v[188:191], v[152:153], off offset:3072
	global_load_dwordx4 v[192:195], v[156:157], off
	global_load_dwordx4 v[196:199], v[156:157], off offset:1024
	global_load_dwordx4 v[200:203], v[156:157], off offset:2048
	global_load_dwordx4 v[204:207], v[156:157], off offset:3072
	global_load_dwordx4 v[208:211], v[154:155], off
	global_load_dwordx4 v[212:215], v[154:155], off offset:1024
	global_load_dwordx4 v[216:219], v[154:155], off offset:2048
	global_load_dwordx4 v[220:223], v[154:155], off offset:3072
	global_load_dwordx4 v[224:227], v[158:159], off
	global_load_dwordx4 v[228:231], v[158:159], off offset:1024
	global_load_dwordx4 v[144:147], v[158:159], off offset:2048
	global_load_dwordx4 v[148:151], v[158:159], off offset:3072
; __device__ __forceinline__ unsigned cvt_pk_bf16(float lo, float hi) { unsigned r; asm volatile("v_cvt_pk_bf16_f32 %0, %1, %2" : "=v"(r) : "v"(lo), "v"(hi)); return r; }
; __device__ __forceinline__ void phase_norm(const float* xin, const float* g, const float* mod, int shift_off, int scale_off, bf16_t* hout) {
;     ...
;     for (int row = blockIdx.x * 8 + wid; row < NTOK; row += nw) {
;         const int b = row >> 13;
;         const float* xr = xin + (size_t)row * DM;
;         f32x4 v[8]; float ss = 0.f;
; #pragma unroll
;         for (int i = 0; i < 8; ++i) { v[i] = *(const f32x4*)(xr + i * 256 + lane * 4); ss += v[i][0] * v[i][0] + v[i][1] * v[i][1] + v[i][2] * v[i][2] + v[i][3] * v[i][3]; }
;         ss = wave_sum(ss);
;         const float rstd = rsqrtf(ss * (1.0f / DM) + 1e-6f);
;         const float* mb = mod + (size_t)b * 6 * DM;
; #pragma unroll
;         for (int i = 0; i < 8; ++i) {
;             const int col = i * 256 + lane * 4;
;             const f32x4 g4 = *(const f32x4*)(g + col), sc4 = *(const f32x4*)(mb + scale_off + col), sh4 = *(const f32x4*)(mb + shift_off + col);
;             f32x4 y = (v[i] * rstd) * g4; y = y * (sc4 + 1.0f) + sh4;
;             u32x2 w; w.x = cvt_pk_bf16(y[0], y[1]); w.y = cvt_pk_bf16(y[2], y[3]);
;             *(u32x2*)(hout + (size_t)row * DM + col) = w;
;         }
;     }
.Lnorm2_params_ok:
	global_load_dwordx4 v[72:75], v[44:45], off offset:-4096
	global_load_dwordx4 v[24:27], v[44:45], off offset:-3072
	global_load_dwordx4 v[20:23], v[44:45], off offset:-2048
	global_load_dwordx4 v[16:19], v[44:45], off offset:-1024
	global_load_dwordx4 v[12:15], v[44:45], off
	global_load_dwordx4 v[8:11], v[44:45], off offset:1024
	global_load_dwordx4 v[4:7], v[44:45], off offset:2048
	global_load_dwordx4 v[0:3], v[44:45], off offset:3072
	v_add_u32_e32 v30, s48, v30
	v_lshl_add_u64 v[44:45], v[44:45], 0, s[52:53]
	s_waitcnt vmcnt(7)
	v_mul_f32_e32 v31, v72, v72
	v_fmac_f32_e32 v31, v73, v73
	v_fmac_f32_e32 v31, v74, v74
	v_fmac_f32_e32 v31, v75, v75
	s_waitcnt vmcnt(6)
	v_mul_f32_e32 v175, v24, v24
	v_fmac_f32_e32 v175, v25, v25
	v_fmac_f32_e32 v175, v26, v26
	v_fmac_f32_e32 v175, v27, v27
	s_waitcnt vmcnt(5)
	v_fmac_f32_e32 v31, v20, v20
	v_fmac_f32_e32 v31, v21, v21
	v_fmac_f32_e32 v31, v22, v22
	v_fmac_f32_e32 v31, v23, v23
	s_waitcnt vmcnt(4)
	v_fmac_f32_e32 v175, v16, v16
	v_fmac_f32_e32 v175, v17, v17
	v_fmac_f32_e32 v175, v18, v18
	v_fmac_f32_e32 v175, v19, v19
	s_waitcnt vmcnt(3)
	v_fmac_f32_e32 v31, v12, v12
	v_fmac_f32_e32 v31, v13, v13
	v_fmac_f32_e32 v31, v14, v14
	v_fmac_f32_e32 v31, v15, v15
	s_waitcnt vmcnt(2)
	v_fmac_f32_e32 v175, v8, v8
	v_fmac_f32_e32 v175, v9, v9
	v_fmac_f32_e32 v175, v10, v10
	v_fmac_f32_e32 v175, v11, v11
	s_waitcnt vmcnt(1)
	v_fmac_f32_e32 v31, v4, v4
	v_fmac_f32_e32 v31, v5, v5
	v_fmac_f32_e32 v31, v6, v6
	v_fmac_f32_e32 v31, v7, v7
	s_waitcnt vmcnt(0)
	v_fmac_f32_e32 v175, v0, v0
	v_fmac_f32_e32 v175, v1, v1
	v_fmac_f32_e32 v175, v2, v2
	v_fmac_f32_e32 v175, v3, v3
	v_add_f32_e32 v31, v31, v175
	ds_bpermute_b32 v64, v66, v31
	s_waitcnt lgkmcnt(0)
	v_add_f32_e32 v31, v31, v64
	ds_bpermute_b32 v64, v67, v31
	s_waitcnt lgkmcnt(0)
	v_add_f32_e32 v31, v31, v64
	ds_bpermute_b32 v64, v68, v31
	s_waitcnt lgkmcnt(0)
	v_add_f32_e32 v31, v31, v64
	ds_bpermute_b32 v64, v69, v31
	s_waitcnt lgkmcnt(0)
	v_add_f32_e32 v31, v31, v64
	ds_bpermute_b32 v64, v70, v31
	s_waitcnt lgkmcnt(0)
	v_add_f32_e32 v31, v31, v64
	ds_bpermute_b32 v64, v71, v31
	s_waitcnt lgkmcnt(0)
	v_add_f32_e32 v31, v31, v64
	v_fmamk_f32 v31, v31, 0x3a000000, v65
	v_mul_f32_e32 v64, 0x4b800000, v31
	v_cmp_gt_f32_e32 vcc, s31, v31
	s_nop 1
	v_cndmask_b32_e32 v31, v31, v64, vcc
	v_rsq_f32_e32 v31, v31
	s_nop 0
	v_mul_f32_e32 v64, 0x45800000, v31
	v_cndmask_b32_e32 v64, v31, v64, vcc
	v_pk_mul_f32 v[72:73], v[72:73], v[64:65] op_sel_hi:[1,0]
	v_pk_mul_f32 v[74:75], v[74:75], v[64:65] op_sel_hi:[1,0]
	v_pk_mul_f32 v[72:73], v[112:113], v[72:73]
	v_pk_mul_f32 v[74:75], v[114:115], v[74:75]
	v_pk_add_f32 v[164:165], v[176:177], 1.0 op_sel_hi:[1,0]
	v_pk_add_f32 v[110:111], v[178:179], 1.0 op_sel_hi:[1,0]
	v_pk_fma_f32 v[72:73], v[164:165], v[72:73], v[208:209]
	v_pk_fma_f32 v[74:75], v[110:111], v[74:75], v[210:211]
	v_cvt_pk_bf16_f32 v72, v72, v73
	v_cvt_pk_bf16_f32 v73, v74, v75
	global_store_dwordx2 v[42:43], v[72:73], off
	v_pk_mul_f32 v[24:25], v[24:25], v[64:65] op_sel_hi:[1,0]
	v_pk_mul_f32 v[26:27], v[26:27], v[64:65] op_sel_hi:[1,0]
	v_pk_mul_f32 v[24:25], v[116:117], v[24:25]
	v_pk_mul_f32 v[26:27], v[118:119], v[26:27]
	v_pk_add_f32 v[164:165], v[180:181], 1.0 op_sel_hi:[1,0]
	v_pk_add_f32 v[110:111], v[182:183], 1.0 op_sel_hi:[1,0]
	v_pk_fma_f32 v[24:25], v[164:165], v[24:25], v[212:213]
	v_pk_fma_f32 v[26:27], v[110:111], v[26:27], v[214:215]
	v_cvt_pk_bf16_f32 v24, v24, v25
	v_cvt_pk_bf16_f32 v25, v26, v27
	global_store_dwordx2 v[42:43], v[24:25], off offset:512
	v_pk_mul_f32 v[20:21], v[20:21], v[64:65] op_sel_hi:[1,0]
	v_pk_mul_f32 v[22:23], v[22:23], v[64:65] op_sel_hi:[1,0]
	v_pk_mul_f32 v[20:21], v[120:121], v[20:21]
	v_pk_mul_f32 v[22:23], v[122:123], v[22:23]
	v_pk_add_f32 v[164:165], v[184:185], 1.0 op_sel_hi:[1,0]
	v_pk_add_f32 v[110:111], v[186:187], 1.0 op_sel_hi:[1,0]
	v_pk_fma_f32 v[20:21], v[164:165], v[20:21], v[216:217]
	v_pk_fma_f32 v[22:23], v[110:111], v[22:23], v[218:219]
	v_cvt_pk_bf16_f32 v20, v20, v21
	v_cvt_pk_bf16_f32 v21, v22, v23
	global_store_dwordx2 v[42:43], v[20:21], off offset:1024
	v_pk_mul_f32 v[16:17], v[16:17], v[64:65] op_sel_hi:[1,0]
	v_pk_mul_f32 v[18:19], v[18:19], v[64:65] op_sel_hi:[1,0]
	v_pk_mul_f32 v[16:17], v[124:125], v[16:17]
	v_pk_mul_f32 v[18:19], v[126:127], v[18:19]
	v_pk_add_f32 v[164:165], v[188:189], 1.0 op_sel_hi:[1,0]
	v_pk_add_f32 v[110:111], v[190:191], 1.0 op_sel_hi:[1,0]
	v_pk_fma_f32 v[16:17], v[164:165], v[16:17], v[220:221]
	v_pk_fma_f32 v[18:19], v[110:111], v[18:19], v[222:223]
	v_cvt_pk_bf16_f32 v16, v16, v17
	v_cvt_pk_bf16_f32 v17, v18, v19
	global_store_dwordx2 v[42:43], v[16:17], off offset:1536
	v_pk_mul_f32 v[12:13], v[12:13], v[64:65] op_sel_hi:[1,0]
	v_pk_mul_f32 v[14:15], v[14:15], v[64:65] op_sel_hi:[1,0]
	v_pk_mul_f32 v[12:13], v[128:129], v[12:13]
	v_pk_mul_f32 v[14:15], v[130:131], v[14:15]
	v_pk_add_f32 v[164:165], v[192:193], 1.0 op_sel_hi:[1,0]
	v_pk_add_f32 v[110:111], v[194:195], 1.0 op_sel_hi:[1,0]
	v_pk_fma_f32 v[12:13], v[164:165], v[12:13], v[224:225]
	v_pk_fma_f32 v[14:15], v[110:111], v[14:15], v[226:227]
	v_cvt_pk_bf16_f32 v12, v12, v13
	v_cvt_pk_bf16_f32 v13, v14, v15
	global_store_dwordx2 v[42:43], v[12:13], off offset:2048
	v_pk_mul_f32 v[8:9], v[8:9], v[64:65] op_sel_hi:[1,0]
	v_pk_mul_f32 v[10:11], v[10:11], v[64:65] op_sel_hi:[1,0]
	v_pk_mul_f32 v[8:9], v[132:133], v[8:9]
	v_pk_mul_f32 v[10:11], v[134:135], v[10:11]
	v_pk_add_f32 v[164:165], v[196:197], 1.0 op_sel_hi:[1,0]
	v_pk_add_f32 v[110:111], v[198:199], 1.0 op_sel_hi:[1,0]
	v_pk_fma_f32 v[8:9], v[164:165], v[8:9], v[228:229]
	v_pk_fma_f32 v[10:11], v[110:111], v[10:11], v[230:231]
	v_cvt_pk_bf16_f32 v8, v8, v9
	v_cvt_pk_bf16_f32 v9, v10, v11
	global_store_dwordx2 v[42:43], v[8:9], off offset:2560
	v_pk_mul_f32 v[4:5], v[4:5], v[64:65] op_sel_hi:[1,0]
	v_pk_mul_f32 v[6:7], v[6:7], v[64:65] op_sel_hi:[1,0]
	v_pk_mul_f32 v[4:5], v[136:137], v[4:5]
	v_pk_mul_f32 v[6:7], v[138:139], v[6:7]
	v_pk_add_f32 v[164:165], v[200:201], 1.0 op_sel_hi:[1,0]
	v_pk_add_f32 v[110:111], v[202:203], 1.0 op_sel_hi:[1,0]
	v_pk_fma_f32 v[4:5], v[164:165], v[4:5], v[144:145]
	v_pk_fma_f32 v[6:7], v[110:111], v[6:7], v[146:147]
	v_cvt_pk_bf16_f32 v4, v4, v5
	v_cvt_pk_bf16_f32 v5, v6, v7
	global_store_dwordx2 v[42:43], v[4:5], off offset:3072
	v_pk_mul_f32 v[0:1], v[0:1], v[64:65] op_sel_hi:[1,0]
	v_pk_mul_f32 v[2:3], v[2:3], v[64:65] op_sel_hi:[1,0]
	v_pk_mul_f32 v[0:1], v[140:141], v[0:1]
	v_pk_mul_f32 v[2:3], v[142:143], v[2:3]
	v_pk_add_f32 v[164:165], v[204:205], 1.0 op_sel_hi:[1,0]
	v_pk_add_f32 v[110:111], v[206:207], 1.0 op_sel_hi:[1,0]
	v_pk_fma_f32 v[0:1], v[164:165], v[0:1], v[148:149]
	v_pk_fma_f32 v[2:3], v[110:111], v[2:3], v[150:151]
	v_cvt_pk_bf16_f32 v0, v0, v1
	v_cvt_pk_bf16_f32 v1, v2, v3
	global_store_dwordx2 v[42:43], v[0:1], off offset:3584
	v_cmp_lt_i32_e32 vcc, s34, v30
	s_or_b64 s[8:9], vcc, s[8:9]
	v_lshl_add_u64 v[42:43], v[42:43], 0, s[50:51]
	s_andn2_b64 exec, exec, s[8:9]
	s_cbranch_execnz .LBB0_1898
	s_branch .LBB0_1895

; #define PG8_LAS __attribute__((address_space(3)))
; #define LAS __attribute__((address_space(3)))
; #define PHASE_P(name) KParams* name##_ptr = (KParams*)__builtin_amdgcn_kernarg_segment_ptr(); asm volatile("" : "+s"(name##_ptr)); KParams& name = *name##_ptr
; __global__ void __launch_bounds__(NTHREADS, 2) fwd_megakernel(ParamsT p_unused) {
;     extern __shared__ __attribute__((aligned(16))) unsigned char smem[];
;     cg::grid_group grid = cg::this_grid();
;     const int G = gridDim.x;
;     PG8_LAS unsigned char* lds = (PG8_LAS unsigned char*)smem;
;     ...
;     const unsigned repm = ((KParams*)__builtin_amdgcn_kernarg_segment_ptr())->repmask;
;     volatile LAS unsigned* xst = (volatile LAS unsigned*)(lds + LDS_PHASE);
;     if (threadIdx.x == 0) { xst[0] = 0u; xst[1] = 0u; }
;     __syncthreads();
;     { PHASE_P(pb); (void)xcd_barrier_post((unsigned*)(pb.ws + WS_BAR), xst); }
	.amdhsa_kernel _Z14fwd_megakernel7ParamsT
		.amdhsa_group_segment_fixed_size 0
		.amdhsa_private_segment_fixed_size 0
		.amdhsa_kernarg_size 400
		.amdhsa_user_sgpr_count 2
		.amdhsa_user_sgpr_dispatch_ptr 0
		.amdhsa_user_sgpr_queue_ptr 0
		.amdhsa_user_sgpr_kernarg_segment_ptr 1
		.amdhsa_user_sgpr_dispatch_id 0
		.amdhsa_user_sgpr_kernarg_preload_length 0
		.amdhsa_user_sgpr_kernarg_preload_offset 0
		.amdhsa_user_sgpr_private_segment_size 0
		.amdhsa_uses_dynamic_stack 0
		.amdhsa_enable_private_segment 0
		.amdhsa_system_sgpr_workgroup_id_x 1
		.amdhsa_system_sgpr_workgroup_id_y 0
		.amdhsa_system_sgpr_workgroup_id_z 0
		.amdhsa_system_sgpr_workgroup_info 0
		.amdhsa_system_vgpr_workitem_id 2
		.amdhsa_next_free_vgpr 235
		.amdhsa_next_free_sgpr 100
		.amdhsa_accum_offset 236
		.amdhsa_reserve_vcc 1
		.amdhsa_float_round_mode_32 0
		.amdhsa_float_round_mode_16_64 0
		.amdhsa_float_denorm_mode_32 3
		.amdhsa_float_denorm_mode_16_64 3
		.amdhsa_dx10_clamp 1
		.amdhsa_ieee_mode 1
		.amdhsa_fp16_overflow 0
		.amdhsa_tg_split 0
		.amdhsa_exception_fp_ieee_invalid_op 0
		.amdhsa_exception_fp_denorm_src 0
		.amdhsa_exception_fp_ieee_div_zero 0
		.amdhsa_exception_fp_ieee_overflow 0
		.amdhsa_exception_fp_ieee_underflow 0
		.amdhsa_exception_fp_ieee_inexact 0
		.amdhsa_exception_int_div_zero 0
	.end_amdhsa_kernel

; #define PG8_LAS __attribute__((address_space(3)))
; #define LAS __attribute__((address_space(3)))
; #define PHASE_P(name) KParams* name##_ptr = (KParams*)__builtin_amdgcn_kernarg_segment_ptr(); asm volatile("" : "+s"(name##_ptr)); KParams& name = *name##_ptr
; __global__ void __launch_bounds__(NTHREADS, 2) fwd_megakernel(ParamsT p_unused) {
;     extern __shared__ __attribute__((aligned(16))) unsigned char smem[];
;     cg::grid_group grid = cg::this_grid();
;     const int G = gridDim.x;
;     PG8_LAS unsigned char* lds = (PG8_LAS unsigned char*)smem;
;     ...
;     const unsigned repm = ((KParams*)__builtin_amdgcn_kernarg_segment_ptr())->repmask;
;     volatile LAS unsigned* xst = (volatile LAS unsigned*)(lds + LDS_PHASE);
;     if (threadIdx.x == 0) { xst[0] = 0u; xst[1] = 0u; }
;     __syncthreads();
;     { PHASE_P(pb); (void)xcd_barrier_post((unsigned*)(pb.ws + WS_BAR), xst); }
amdhsa.kernels:
  - .agpr_count:     0
    .args:
      - .offset:         0
        .size:           144
        .value_kind:     by_value
      - .offset:         144
        .size:           4
        .value_kind:     hidden_block_count_x
      - .offset:         148
        .size:           4
        .value_kind:     hidden_block_count_y
      - .offset:         152
        .size:           4
        .value_kind:     hidden_block_count_z
      - .offset:         156
        .size:           2
        .value_kind:     hidden_group_size_x
      - .offset:         158
        .size:           2
        .value_kind:     hidden_group_size_y
      - .offset:         160
        .size:           2
        .value_kind:     hidden_group_size_z
      - .offset:         162
        .size:           2
        .value_kind:     hidden_remainder_x
      - .offset:         164
        .size:           2
        .value_kind:     hidden_remainder_y
      - .offset:         166
        .size:           2
        .value_kind:     hidden_remainder_z
      - .offset:         184
        .size:           8
        .value_kind:     hidden_global_offset_x
      - .offset:         192
        .size:           8
        .value_kind:     hidden_global_offset_y
      - .offset:         200
        .size:           8
        .value_kind:     hidden_global_offset_z
      - .offset:         208
        .size:           2
        .value_kind:     hidden_grid_dims
      - .offset:         232
        .size:           8
        .value_kind:     hidden_multigrid_sync_arg
      - .offset:         264
        .size:           4
        .value_kind:     hidden_dynamic_lds_size
    .group_segment_fixed_size: 0
    .kernarg_segment_align: 8
    .kernarg_segment_size: 400
    .language:       OpenCL C
    .language_version:
      - 2
      - 0
    .max_flat_workgroup_size: 512
    .name:           _Z14fwd_megakernel7ParamsT
    .private_segment_fixed_size: 0
    .sgpr_count:     106
    .sgpr_spill_count: 5
    .symbol:         _Z14fwd_megakernel7ParamsT.kd
    .uniform_work_group_size: 1
    .uses_dynamic_stack: false
    .vgpr_count:     235
    .vgpr_spill_count: 0
    .wavefront_size: 64
